# adds E26: group-2 band attention epilogue issues the mixing operands' 16 loads at the top of the epilogue instead of right before use, stacked on E24
# baseline (speedup 1.0000x reference)
.LBB0_704:
	s_or_b64 exec, exec, s[0:1]
	s_mov_b32 s12, s70
	s_ashr_i32 s13, s70, 31
	s_lshl_b64 s[12:13], s[12:13], 11
	s_add_u32 s12, s10, s12
	s_addc_u32 s13, s11, s13
	v_lshlrev_b32_e32 v70, 1, v163
	v_and_b32_e32 v70, 0x70, v70
	v_mov_b32_e32 v71, 0
	v_lshl_add_u64 v[68:69], s[12:13], 0, v[70:71]
	s_mov_b32 s12, 0xfd000000
	s_mov_b32 s13, -1
	v_lshl_add_u64 v[68:69], v[68:69], 0, s[12:13]
	v_lshlrev_b32_e32 v70, 11, v162
	v_mov_b32_e32 v76, v160
	v_lshl_add_u64 v[72:73], v[68:69], 0, v[70:71]
	global_load_dwordx4 v[80:83], v[72:73], off
	v_add_co_u32_e32 v72, vcc, 0x1800000, v72
	s_nop 1
	v_addc_co_u32_e32 v73, vcc, 0, v73, vcc
	global_load_dwordx4 v[84:87], v[72:73], off
	v_ashrrev_i32_e32 v77, 31, v76
	v_lshlrev_b64 v[74:75], 10, v[76:77]
	v_lshl_add_u64 v[74:75], s[6:7], 0, v[74:75]
	v_add_co_u32_e32 v72, vcc, 0xffc00000, v74
	s_nop 1
	v_addc_co_u32_e32 v73, vcc, -1, v75, vcc
	global_load_dword v112, v[72:73], off
	v_add_co_u32_e32 v72, vcc, 0xffe00000, v74
	s_nop 1
	v_addc_co_u32_e32 v73, vcc, -1, v75, vcc
	global_load_dword v113, v[72:73], off
	v_or_b32_e32 v70, 8, v162
	v_or_b32_e32 v76, s70, v70
	v_lshlrev_b32_e32 v70, 11, v70
	v_lshl_add_u64 v[72:73], v[68:69], 0, v[70:71]
	global_load_dwordx4 v[88:91], v[72:73], off
	v_add_co_u32_e32 v72, vcc, 0x1800000, v72
	s_nop 1
	v_addc_co_u32_e32 v73, vcc, 0, v73, vcc
	global_load_dwordx4 v[92:95], v[72:73], off
	v_ashrrev_i32_e32 v77, 31, v76
	v_lshlrev_b64 v[74:75], 10, v[76:77]
	v_lshl_add_u64 v[74:75], s[6:7], 0, v[74:75]
	v_add_co_u32_e32 v72, vcc, 0xffc00000, v74
	s_nop 1
	v_addc_co_u32_e32 v73, vcc, -1, v75, vcc
	global_load_dword v114, v[72:73], off
	v_add_co_u32_e32 v72, vcc, 0xffe00000, v74
	s_nop 1
	v_addc_co_u32_e32 v73, vcc, -1, v75, vcc
	global_load_dword v115, v[72:73], off
	v_or_b32_e32 v70, 16, v162
	v_or_b32_e32 v76, s70, v70
	v_lshlrev_b32_e32 v70, 11, v70
	v_lshl_add_u64 v[72:73], v[68:69], 0, v[70:71]
	global_load_dwordx4 v[96:99], v[72:73], off
	v_add_co_u32_e32 v72, vcc, 0x1800000, v72
	s_nop 1
	v_addc_co_u32_e32 v73, vcc, 0, v73, vcc
	global_load_dwordx4 v[100:103], v[72:73], off
	v_ashrrev_i32_e32 v77, 31, v76
	v_lshlrev_b64 v[74:75], 10, v[76:77]
	v_lshl_add_u64 v[74:75], s[6:7], 0, v[74:75]
	v_add_co_u32_e32 v72, vcc, 0xffc00000, v74
	s_nop 1
	v_addc_co_u32_e32 v73, vcc, -1, v75, vcc
	global_load_dword v116, v[72:73], off
	v_add_co_u32_e32 v72, vcc, 0xffe00000, v74
	s_nop 1
	v_addc_co_u32_e32 v73, vcc, -1, v75, vcc
	global_load_dword v117, v[72:73], off
	v_or_b32_e32 v70, 24, v162
	v_or_b32_e32 v76, s70, v70
	v_lshlrev_b32_e32 v70, 11, v70
	v_lshl_add_u64 v[72:73], v[68:69], 0, v[70:71]
	global_load_dwordx4 v[104:107], v[72:73], off
	v_add_co_u32_e32 v72, vcc, 0x1800000, v72
	s_nop 1
	v_addc_co_u32_e32 v73, vcc, 0, v73, vcc
	global_load_dwordx4 v[108:111], v[72:73], off
	v_ashrrev_i32_e32 v77, 31, v76
	v_lshlrev_b64 v[74:75], 10, v[76:77]
	v_lshl_add_u64 v[74:75], s[6:7], 0, v[74:75]
	v_add_co_u32_e32 v72, vcc, 0xffc00000, v74
	s_nop 1
	v_addc_co_u32_e32 v73, vcc, -1, v75, vcc
	global_load_dword v118, v[72:73], off
	v_add_co_u32_e32 v72, vcc, 0xffe00000, v74
	s_nop 1
	v_addc_co_u32_e32 v73, vcc, -1, v75, vcc
	global_load_dword v119, v[72:73], off
	s_waitcnt lgkmcnt(0)
	v_lshl_add_u32 v40, v167, 2, s2
	ds_read_b128 v[32:35], v40 offset:49280
	ds_read_b128 v[36:39], v40 offset:49312
	s_add_i32 s0, s18, 0
	v_lshlrev_b32_e32 v49, 9, v166
	s_ashr_i32 s71, s70, 31
	s_waitcnt lgkmcnt(1)
	v_rcp_f32_e32 v41, v32
	v_rcp_f32_e32 v42, v33
	v_rcp_f32_e32 v43, v34
	v_rcp_f32_e32 v44, v35
	ds_read_b128 v[32:35], v40 offset:49344
	v_mul_f32_e32 v0, v0, v41
	v_cvt_pk_bf16_f32 v0, v0, s0
	s_waitcnt lgkmcnt(1)
	v_rcp_f32_e32 v36, v36
	v_rcp_f32_e32 v37, v37
	s_waitcnt lgkmcnt(0)
	v_rcp_f32_e32 v45, v32
	v_rcp_f32_e32 v46, v33
	v_rcp_f32_e32 v47, v34
	v_rcp_f32_e32 v48, v35
	ds_read_b128 v[32:35], v40 offset:49376
	v_lshlrev_b32_e32 v40, 1, v165
	v_add3_u32 v40, s0, v40, v49
	ds_write_b16 v40, v0 offset:51200
	v_mul_f32_e32 v0, v16, v41
	v_cvt_pk_bf16_f32 v0, v0, s0
	ds_write_b16 v40, v0 offset:51264
	v_mul_f32_e32 v0, v1, v42
	v_cvt_pk_bf16_f32 v0, v0, s0
	ds_write_b16 v40, v0 offset:51328
	v_mul_f32_e32 v0, v17, v42
	v_cvt_pk_bf16_f32 v0, v0, s0
	ds_write_b16 v40, v0 offset:51392
	v_mul_f32_e32 v0, v2, v43
	v_cvt_pk_bf16_f32 v0, v0, s0
	ds_write_b16 v40, v0 offset:51456
	v_mul_f32_e32 v0, v18, v43
	v_cvt_pk_bf16_f32 v0, v0, s0
	ds_write_b16 v40, v0 offset:51520
	v_mul_f32_e32 v0, v3, v44
	v_cvt_pk_bf16_f32 v0, v0, s0
	ds_write_b16 v40, v0 offset:51584
	v_mul_f32_e32 v0, v19, v44
	v_cvt_pk_bf16_f32 v0, v0, s0
	ds_write_b16 v40, v0 offset:51648
	v_mul_f32_e32 v0, v4, v36
	v_cvt_pk_bf16_f32 v0, v0, s0
	ds_write_b16 v40, v0 offset:52224
	v_mul_f32_e32 v0, v20, v36
	v_cvt_pk_bf16_f32 v0, v0, s0
	v_rcp_f32_e32 v38, v38
	ds_write_b16 v40, v0 offset:52288
	v_mul_f32_e32 v0, v5, v37
	v_cvt_pk_bf16_f32 v0, v0, s0
	ds_write_b16 v40, v0 offset:52352
	v_mul_f32_e32 v0, v21, v37
	v_cvt_pk_bf16_f32 v0, v0, s0
	v_rcp_f32_e32 v39, v39
	ds_write_b16 v40, v0 offset:52416
	v_mul_f32_e32 v0, v6, v38
	v_cvt_pk_bf16_f32 v0, v0, s0
	ds_write_b16 v40, v0 offset:52480
	v_mul_f32_e32 v0, v22, v38
	v_cvt_pk_bf16_f32 v0, v0, s0
	ds_write_b16 v40, v0 offset:52544
	v_mul_f32_e32 v0, v7, v39
	v_cvt_pk_bf16_f32 v0, v0, s0
	ds_write_b16 v40, v0 offset:52608
	v_mul_f32_e32 v0, v23, v39
	v_cvt_pk_bf16_f32 v0, v0, s0
	ds_write_b16 v40, v0 offset:52672
	v_mul_f32_e32 v0, v8, v45
	v_cvt_pk_bf16_f32 v0, v0, s0
	ds_write_b16 v40, v0 offset:53248
	v_mul_f32_e32 v0, v24, v45
	v_cvt_pk_bf16_f32 v0, v0, s0
	ds_write_b16 v40, v0 offset:53312
	v_mul_f32_e32 v0, v9, v46
	v_cvt_pk_bf16_f32 v0, v0, s0
	ds_write_b16 v40, v0 offset:53376
	v_mul_f32_e32 v0, v25, v46
	v_cvt_pk_bf16_f32 v0, v0, s0
	ds_write_b16 v40, v0 offset:53440
	v_mul_f32_e32 v0, v10, v47
	v_cvt_pk_bf16_f32 v0, v0, s0
	ds_write_b16 v40, v0 offset:53504
	v_mul_f32_e32 v0, v26, v47
	v_cvt_pk_bf16_f32 v0, v0, s0
	s_waitcnt lgkmcnt(14)
	v_rcp_f32_e32 v32, v32
	ds_write_b16 v40, v0 offset:53568
	v_mul_f32_e32 v0, v11, v48
	v_cvt_pk_bf16_f32 v0, v0, s0
	ds_write_b16 v40, v0 offset:53632
	v_mul_f32_e32 v0, v27, v48
	v_cvt_pk_bf16_f32 v0, v0, s0
	v_rcp_f32_e32 v33, v33
	ds_write_b16 v40, v0 offset:53696
	v_mul_f32_e32 v0, v12, v32
	v_cvt_pk_bf16_f32 v0, v0, s0
	ds_write_b16 v40, v0 offset:54272
	v_mul_f32_e32 v0, v28, v32
	v_cvt_pk_bf16_f32 v0, v0, s0
	v_rcp_f32_e32 v34, v34
	ds_write_b16 v40, v0 offset:54336
	v_mul_f32_e32 v0, v13, v33
	v_cvt_pk_bf16_f32 v0, v0, s0
	ds_write_b16 v40, v0 offset:54400
	v_mul_f32_e32 v0, v29, v33
	v_cvt_pk_bf16_f32 v0, v0, s0
	v_rcp_f32_e32 v35, v35
	ds_write_b16 v40, v0 offset:54464
	v_mul_f32_e32 v0, v14, v34
	v_cvt_pk_bf16_f32 v0, v0, s0
	ds_write_b16 v40, v0 offset:54528
	v_mul_f32_e32 v0, v30, v34
	v_cvt_pk_bf16_f32 v0, v0, s0
	ds_write_b16 v40, v0 offset:54592
	v_mul_f32_e32 v0, v15, v35
	v_cvt_pk_bf16_f32 v0, v0, s0
	ds_write_b16 v40, v0 offset:54656
	v_mul_f32_e32 v0, v31, v35
	v_cvt_pk_bf16_f32 v0, v0, s0
	s_lshl_b64 s[12:13], s[70:71], 11
	ds_write_b16 v40, v0 offset:54720
	s_add_u32 s10, s10, s12
	v_lshlrev_b32_e32 v0, 1, v163
	s_addc_u32 s11, s11, s13
	v_and_b32_e32 v192, 0x70, v0
	v_lshl_add_u64 v[0:1], s[10:11], 0, v[192:193]
	s_mov_b32 s10, 0xfd000000
	s_mov_b32 s11, -1
	v_lshl_add_u64 v[0:1], v[0:1], 0, s[10:11]
	v_lshlrev_b32_e32 v2, 11, v162
	v_mov_b32_e32 v3, v193
	s_waitcnt lgkmcnt(0)
	v_lshl_add_u64 v[2:3], v[0:1], 0, v[2:3]
	s_mov_b32 s1, 0x1800000
	s_waitcnt vmcnt(0)
	v_mov_b64_e32 v[24:25], v[80:81]
	v_mov_b64_e32 v[26:27], v[82:83]
	v_add_co_u32_e32 v2, vcc, s1, v2
	v_ashrrev_i32_e32 v161, 31, v160
	s_nop 0
	v_addc_co_u32_e32 v3, vcc, 0, v3, vcc
	v_mov_b64_e32 v[28:29], v[84:85]
	v_mov_b64_e32 v[30:31], v[86:87]
	v_lshlrev_b64 v[2:3], 10, v[160:161]
	v_lshl_add_u64 v[2:3], s[6:7], 0, v[2:3]
	s_mov_b32 s3, 0xffc00000
	v_add_co_u32_e32 v4, vcc, s3, v2
	s_mov_b32 s10, 0xffe00000
	s_nop 0
	v_addc_co_u32_e32 v5, vcc, -1, v3, vcc
	v_add_co_u32_e32 v2, vcc, s10, v2
	v_mov_b32_e32 v49, v112
	s_nop 0
	v_addc_co_u32_e32 v3, vcc, -1, v3, vcc
	v_mov_b32_e32 v54, v113
	v_or_b32_e32 v57, 8, v162
	v_lshlrev_b32_e32 v2, 11, v57
	v_mov_b32_e32 v3, v193
	v_lshl_add_u64 v[2:3], v[0:1], 0, v[2:3]
	v_mov_b64_e32 v[16:17], v[88:89]
	v_mov_b64_e32 v[18:19], v[90:91]
	v_add_co_u32_e32 v2, vcc, s1, v2
	v_or_b32_e32 v38, s70, v57
	s_nop 0
	v_addc_co_u32_e32 v3, vcc, 0, v3, vcc
	v_ashrrev_i32_e32 v39, 31, v38
	v_mov_b64_e32 v[20:21], v[92:93]
	v_mov_b64_e32 v[22:23], v[94:95]
	v_lshlrev_b64 v[2:3], 10, v[38:39]
	v_lshl_add_u64 v[2:3], s[6:7], 0, v[2:3]
	v_add_co_u32_e32 v4, vcc, s3, v2
	v_or_b32_e32 v47, 16, v162
	s_nop 0
	v_addc_co_u32_e32 v5, vcc, -1, v3, vcc
	v_add_co_u32_e32 v2, vcc, s10, v2
	v_mov_b32_e32 v64, v114
	s_nop 0
	v_addc_co_u32_e32 v3, vcc, -1, v3, vcc
	v_mov_b32_e32 v65, v115
	v_lshlrev_b32_e32 v2, 11, v47
	v_mov_b32_e32 v3, v193
	v_lshl_add_u64 v[2:3], v[0:1], 0, v[2:3]
	v_mov_b64_e32 v[8:9], v[96:97]
	v_mov_b64_e32 v[10:11], v[98:99]
	v_add_co_u32_e32 v2, vcc, s1, v2
	v_or_b32_e32 v36, s70, v47
	s_nop 0
	v_addc_co_u32_e32 v3, vcc, 0, v3, vcc
	v_ashrrev_i32_e32 v37, 31, v36
	v_mov_b64_e32 v[12:13], v[100:101]
	v_mov_b64_e32 v[14:15], v[102:103]
	v_lshlrev_b64 v[2:3], 10, v[36:37]
	v_lshl_add_u64 v[2:3], s[6:7], 0, v[2:3]
	v_add_co_u32_e32 v4, vcc, s3, v2
	v_or_b32_e32 v44, 24, v162
	s_nop 0
	v_addc_co_u32_e32 v5, vcc, -1, v3, vcc
	v_add_co_u32_e32 v2, vcc, s10, v2
	v_mov_b32_e32 v46, v116
	s_nop 0
	v_addc_co_u32_e32 v3, vcc, -1, v3, vcc
	v_mov_b32_e32 v48, v117
	v_lshlrev_b32_e32 v2, 11, v44
	v_mov_b32_e32 v3, v193
	v_or_b32_e32 v32, s70, v44
	v_lshl_add_u64 v[4:5], v[0:1], 0, v[2:3]
	v_ashrrev_i32_e32 v33, 31, v32
	v_mov_b64_e32 v[0:1], v[104:105]
	v_mov_b64_e32 v[2:3], v[106:107]
	v_add_co_u32_e32 v4, vcc, s1, v4
	v_lshlrev_b64 v[34:35], 10, v[32:33]
	s_nop 0
	v_addc_co_u32_e32 v5, vcc, 0, v5, vcc
	v_lshl_add_u64 v[34:35], s[6:7], 0, v[34:35]
	v_add_co_u32_e32 v40, vcc, s3, v34
	v_add_u32_e32 v45, s0, v192
	s_nop 0
	v_addc_co_u32_e32 v41, vcc, -1, v35, vcc
	v_add_co_u32_e32 v34, vcc, s10, v34
	v_mov_b64_e32 v[4:5], v[108:109]
	v_mov_b64_e32 v[6:7], v[110:111]
	s_nop 0
	v_addc_co_u32_e32 v35, vcc, -1, v35, vcc
	v_mov_b32_e32 v42, v118
	v_mov_b32_e32 v43, v119
	v_lshl_add_u32 v40, v162, 7, v45
	ds_read_b128 v[50:53], v40 offset:51200
	v_lshl_add_u32 v40, v162, 2, s2
	v_add_u32_e32 v66, 0xc000, v40
	ds_read2_b32 v[40:41], v66 offset1:8
	s_waitcnt vmcnt(15)
	v_lshlrev_b32_e32 v60, 16, v24
	s_waitcnt vmcnt(14)
	v_and_b32_e32 v61, 0xffff0000, v28
	v_lshlrev_b32_e32 v58, 16, v28
	v_and_b32_e32 v59, 0xffff0000, v24
	s_waitcnt vmcnt(12) lgkmcnt(0)
	v_max3_f32 v56, v49, v54, v40
	v_sub_f32_e32 v49, v49, v56
	v_exp_f32_e32 v55, v49
	v_sub_f32_e32 v49, v54, v56
	v_exp_f32_e32 v54, v49
	v_sub_f32_e32 v40, v40, v56
	v_exp_f32_e32 v49, v40
	v_lshlrev_b32_e32 v62, 16, v50
	v_add_f32_e32 v40, v55, v54
	v_and_b32_e32 v63, 0xffff0000, v50
	v_add_f32_e32 v40, v49, v40
	v_rcp_f32_e32 v40, v40
	v_lshlrev_b32_e32 v28, 16, v25
	v_lshlrev_b32_e32 v50, 16, v51
	v_and_b32_e32 v51, 0xffff0000, v51
	v_pk_mul_f32 v[54:55], v[54:55], v[40:41] op_sel_hi:[1,0]
	v_mul_f32_e32 v56, v49, v40
	v_pk_mul_f32 v[60:61], v[54:55], v[60:61] op_sel:[1,0] op_sel_hi:[0,1]
	v_pk_fma_f32 v[58:59], v[54:55], v[58:59], v[60:61]
	v_lshl_add_u64 v[34:35], s[8:9], 0, v[192:193]
	v_pk_fma_f32 v[58:59], v[56:57], v[62:63], v[58:59] op_sel_hi:[0,1,1]
	v_cvt_pk_bf16_f32 v24, v58, v59
	v_lshlrev_b32_e32 v58, 16, v29
	v_and_b32_e32 v29, 0xffff0000, v29
	v_and_b32_e32 v59, 0xffff0000, v25
	v_pk_mul_f32 v[28:29], v[54:55], v[28:29] op_sel:[1,0] op_sel_hi:[0,1]
	v_pk_fma_f32 v[28:29], v[54:55], v[58:59], v[28:29]
	v_lshlrev_b32_e32 v58, 16, v52
	v_pk_fma_f32 v[28:29], v[56:57], v[50:51], v[28:29] op_sel_hi:[0,1,1]
	v_lshlrev_b32_e32 v50, 16, v26
	v_and_b32_e32 v51, 0xffff0000, v30
	v_cvt_pk_bf16_f32 v25, v28, v29
	v_lshlrev_b32_e32 v28, 16, v30
	v_and_b32_e32 v29, 0xffff0000, v26
	v_pk_mul_f32 v[50:51], v[54:55], v[50:51] op_sel:[1,0] op_sel_hi:[0,1]
	v_and_b32_e32 v59, 0xffff0000, v52
	v_pk_fma_f32 v[28:29], v[54:55], v[28:29], v[50:51]
	v_lshlrev_b32_e32 v30, 16, v27
	v_pk_fma_f32 v[28:29], v[56:57], v[58:59], v[28:29] op_sel_hi:[0,1,1]
	v_cvt_pk_bf16_f32 v26, v28, v29
	v_lshlrev_b32_e32 v28, 16, v31
	v_and_b32_e32 v31, 0xffff0000, v31
	v_and_b32_e32 v29, 0xffff0000, v27
	v_pk_mul_f32 v[30:31], v[54:55], v[30:31] op_sel:[1,0] op_sel_hi:[0,1]
	v_pk_fma_f32 v[28:29], v[54:55], v[28:29], v[30:31]
	v_lshlrev_b32_e32 v30, 16, v53
	v_and_b32_e32 v31, 0xffff0000, v53
	s_waitcnt vmcnt(8)
	v_max3_f32 v40, v64, v65, v41
	v_pk_fma_f32 v[28:29], v[56:57], v[30:31], v[28:29] op_sel_hi:[0,1,1]
	v_sub_f32_e32 v30, v64, v40
	v_exp_f32_e32 v31, v30
	v_sub_f32_e32 v30, v65, v40
	v_exp_f32_e32 v30, v30
	v_sub_f32_e32 v40, v41, v40
	v_exp_f32_e32 v41, v40
	v_cvt_pk_bf16_f32 v27, v28, v29
	v_add_f32_e32 v40, v31, v30
	v_lshlrev_b64 v[28:29], 15, v[160:161]
	v_add_f32_e32 v40, v41, v40
	v_lshl_add_u64 v[28:29], v[34:35], 0, v[28:29]
	v_rcp_f32_e32 v40, v40
	global_store_dwordx4 v[28:29], v[24:27], off
	v_lshlrev_b32_e32 v52, 16, v16
	v_and_b32_e32 v53, 0xffff0000, v20
	v_lshl_add_u32 v24, v57, 7, v45
	ds_read_b128 v[24:27], v24 offset:51200
	ds_read2_b32 v[28:29], v66 offset0:16 offset1:24
	v_pk_mul_f32 v[30:31], v[30:31], v[40:41] op_sel_hi:[1,0]
	v_mul_f32_e32 v50, v41, v40
	v_lshlrev_b32_e32 v40, 16, v20
	v_and_b32_e32 v41, 0xffff0000, v16
	v_pk_mul_f32 v[52:53], v[30:31], v[52:53] op_sel:[1,0] op_sel_hi:[0,1]
	s_waitcnt lgkmcnt(1)
	v_lshlrev_b32_e32 v54, 16, v24
	v_and_b32_e32 v55, 0xffff0000, v24
	v_pk_fma_f32 v[40:41], v[30:31], v[40:41], v[52:53]
	v_lshlrev_b32_e32 v20, 16, v17
	v_pk_fma_f32 v[40:41], v[50:51], v[54:55], v[40:41] op_sel_hi:[0,1,1]
	v_cvt_pk_bf16_f32 v16, v40, v41
	v_lshlrev_b32_e32 v40, 16, v21
	v_and_b32_e32 v21, 0xffff0000, v21
	v_and_b32_e32 v41, 0xffff0000, v17
	v_pk_mul_f32 v[20:21], v[30:31], v[20:21] op_sel:[1,0] op_sel_hi:[0,1]
	v_lshlrev_b32_e32 v24, 16, v25
	v_and_b32_e32 v25, 0xffff0000, v25
	v_pk_fma_f32 v[20:21], v[30:31], v[40:41], v[20:21]
	v_lshlrev_b32_e32 v40, 16, v26
	v_pk_fma_f32 v[20:21], v[50:51], v[24:25], v[20:21] op_sel_hi:[0,1,1]
	v_lshlrev_b32_e32 v24, 16, v18
	v_and_b32_e32 v25, 0xffff0000, v22
	v_cvt_pk_bf16_f32 v17, v20, v21
	v_lshlrev_b32_e32 v20, 16, v22
	v_and_b32_e32 v21, 0xffff0000, v18
	v_pk_mul_f32 v[24:25], v[30:31], v[24:25] op_sel:[1,0] op_sel_hi:[0,1]
	v_and_b32_e32 v41, 0xffff0000, v26
	v_pk_fma_f32 v[20:21], v[30:31], v[20:21], v[24:25]
	v_lshlrev_b32_e32 v22, 16, v19
	v_pk_fma_f32 v[20:21], v[50:51], v[40:41], v[20:21] op_sel_hi:[0,1,1]
	v_cvt_pk_bf16_f32 v18, v20, v21
	v_lshlrev_b32_e32 v20, 16, v23
	v_and_b32_e32 v23, 0xffff0000, v23
	v_and_b32_e32 v21, 0xffff0000, v19
	v_pk_mul_f32 v[22:23], v[30:31], v[22:23] op_sel:[1,0] op_sel_hi:[0,1]
	v_pk_fma_f32 v[20:21], v[30:31], v[20:21], v[22:23]
	v_lshlrev_b32_e32 v22, 16, v27
	v_and_b32_e32 v23, 0xffff0000, v27
	v_pk_fma_f32 v[20:21], v[50:51], v[22:23], v[20:21] op_sel_hi:[0,1,1]
	v_cvt_pk_bf16_f32 v19, v20, v21
	v_lshlrev_b64 v[20:21], 15, v[38:39]
	v_lshl_add_u64 v[20:21], v[34:35], 0, v[20:21]
	s_waitcnt vmcnt(5) lgkmcnt(0)
	v_max3_f32 v22, v46, v48, v28
	global_store_dwordx4 v[20:21], v[16:19], off
	v_sub_f32_e32 v20, v46, v22
	v_exp_f32_e32 v21, v20
	v_sub_f32_e32 v20, v48, v22
	v_exp_f32_e32 v20, v20
	v_sub_f32_e32 v22, v28, v22
	v_exp_f32_e32 v23, v22
	v_lshl_add_u32 v16, v47, 7, v45
	v_add_f32_e32 v22, v21, v20
	ds_read_b128 v[16:19], v16 offset:51200
	v_add_f32_e32 v22, v23, v22
	v_rcp_f32_e32 v22, v22
	v_lshlrev_b32_e32 v26, 16, v8
	v_and_b32_e32 v27, 0xffff0000, v12
	s_waitcnt lgkmcnt(0)
	v_lshlrev_b32_e32 v30, 16, v16
	v_pk_mul_f32 v[20:21], v[20:21], v[22:23] op_sel_hi:[1,0]
	v_mul_f32_e32 v24, v23, v22
	v_lshlrev_b32_e32 v22, 16, v12
	v_and_b32_e32 v23, 0xffff0000, v8
	v_pk_mul_f32 v[26:27], v[20:21], v[26:27] op_sel:[1,0] op_sel_hi:[0,1]
	v_and_b32_e32 v31, 0xffff0000, v16
	v_pk_fma_f32 v[22:23], v[20:21], v[22:23], v[26:27]
	v_lshlrev_b32_e32 v12, 16, v9
	v_pk_fma_f32 v[22:23], v[24:25], v[30:31], v[22:23] op_sel_hi:[0,1,1]
	v_cvt_pk_bf16_f32 v8, v22, v23
	v_lshlrev_b32_e32 v22, 16, v13
	v_and_b32_e32 v13, 0xffff0000, v13
	v_and_b32_e32 v23, 0xffff0000, v9
	v_pk_mul_f32 v[12:13], v[20:21], v[12:13] op_sel:[1,0] op_sel_hi:[0,1]
	v_lshlrev_b32_e32 v16, 16, v17
	v_and_b32_e32 v17, 0xffff0000, v17
	v_pk_fma_f32 v[12:13], v[20:21], v[22:23], v[12:13]
	v_lshlrev_b32_e32 v22, 16, v18
	v_pk_fma_f32 v[12:13], v[24:25], v[16:17], v[12:13] op_sel_hi:[0,1,1]
	v_lshlrev_b32_e32 v16, 16, v10
	v_and_b32_e32 v17, 0xffff0000, v14
	v_cvt_pk_bf16_f32 v9, v12, v13
	v_lshlrev_b32_e32 v12, 16, v14
	v_and_b32_e32 v13, 0xffff0000, v10
	v_pk_mul_f32 v[16:17], v[20:21], v[16:17] op_sel:[1,0] op_sel_hi:[0,1]
	v_and_b32_e32 v23, 0xffff0000, v18
	v_pk_fma_f32 v[12:13], v[20:21], v[12:13], v[16:17]
	v_lshlrev_b32_e32 v14, 16, v11
	v_pk_fma_f32 v[12:13], v[24:25], v[22:23], v[12:13] op_sel_hi:[0,1,1]
	v_cvt_pk_bf16_f32 v10, v12, v13
	v_lshlrev_b32_e32 v12, 16, v15
	v_and_b32_e32 v15, 0xffff0000, v15
	v_and_b32_e32 v13, 0xffff0000, v11
	v_pk_mul_f32 v[14:15], v[20:21], v[14:15] op_sel:[1,0] op_sel_hi:[0,1]
	v_pk_fma_f32 v[12:13], v[20:21], v[12:13], v[14:15]
	v_lshlrev_b32_e32 v14, 16, v19
	v_and_b32_e32 v15, 0xffff0000, v19
	v_pk_fma_f32 v[12:13], v[24:25], v[14:15], v[12:13] op_sel_hi:[0,1,1]
	v_cvt_pk_bf16_f32 v11, v12, v13
	v_lshlrev_b64 v[12:13], 15, v[36:37]
	v_lshl_add_u64 v[12:13], v[34:35], 0, v[12:13]
	s_waitcnt vmcnt(2)
	v_max3_f32 v14, v42, v43, v29
	global_store_dwordx4 v[12:13], v[8:11], off
	v_sub_f32_e32 v12, v42, v14
	v_exp_f32_e32 v13, v12
	v_sub_f32_e32 v12, v43, v14
	v_exp_f32_e32 v12, v12
	v_sub_f32_e32 v14, v29, v14
	v_exp_f32_e32 v15, v14
	v_lshl_add_u32 v8, v44, 7, v45
	v_add_f32_e32 v14, v13, v12
	ds_read_b128 v[8:11], v8 offset:51200
	v_add_f32_e32 v14, v15, v14
	v_rcp_f32_e32 v14, v14
	v_lshlrev_b32_e32 v18, 16, v0
	v_and_b32_e32 v19, 0xffff0000, v4
	s_waitcnt lgkmcnt(0)
	v_lshlrev_b32_e32 v20, 16, v8
	v_pk_mul_f32 v[12:13], v[12:13], v[14:15] op_sel_hi:[1,0]
	v_mul_f32_e32 v16, v15, v14
	v_lshlrev_b32_e32 v14, 16, v4
	v_and_b32_e32 v15, 0xffff0000, v0
	v_pk_mul_f32 v[18:19], v[12:13], v[18:19] op_sel:[1,0] op_sel_hi:[0,1]
	v_and_b32_e32 v21, 0xffff0000, v8
	v_pk_fma_f32 v[14:15], v[12:13], v[14:15], v[18:19]
	v_lshlrev_b32_e32 v4, 16, v1
	v_pk_fma_f32 v[14:15], v[16:17], v[20:21], v[14:15] op_sel_hi:[0,1,1]
	v_cvt_pk_bf16_f32 v0, v14, v15
	v_lshlrev_b32_e32 v14, 16, v5
	v_and_b32_e32 v5, 0xffff0000, v5
	v_and_b32_e32 v15, 0xffff0000, v1
	v_pk_mul_f32 v[4:5], v[12:13], v[4:5] op_sel:[1,0] op_sel_hi:[0,1]
	v_lshlrev_b32_e32 v8, 16, v9
	v_and_b32_e32 v9, 0xffff0000, v9
	v_pk_fma_f32 v[4:5], v[12:13], v[14:15], v[4:5]
	v_lshlrev_b32_e32 v14, 16, v10
	v_pk_fma_f32 v[4:5], v[16:17], v[8:9], v[4:5] op_sel_hi:[0,1,1]
	v_lshlrev_b32_e32 v8, 16, v2
	v_and_b32_e32 v9, 0xffff0000, v6
	v_cvt_pk_bf16_f32 v1, v4, v5
	v_lshlrev_b32_e32 v4, 16, v6
	v_and_b32_e32 v5, 0xffff0000, v2
	v_pk_mul_f32 v[8:9], v[12:13], v[8:9] op_sel:[1,0] op_sel_hi:[0,1]
	v_and_b32_e32 v15, 0xffff0000, v10
	v_pk_fma_f32 v[4:5], v[12:13], v[4:5], v[8:9]
	v_lshlrev_b32_e32 v6, 16, v3
	v_pk_fma_f32 v[4:5], v[16:17], v[14:15], v[4:5] op_sel_hi:[0,1,1]
	v_cvt_pk_bf16_f32 v2, v4, v5
	v_lshlrev_b32_e32 v4, 16, v7
	v_and_b32_e32 v7, 0xffff0000, v7
	v_and_b32_e32 v5, 0xffff0000, v3
	v_pk_mul_f32 v[6:7], v[12:13], v[6:7] op_sel:[1,0] op_sel_hi:[0,1]
	v_pk_fma_f32 v[4:5], v[12:13], v[4:5], v[6:7]
	v_lshlrev_b32_e32 v6, 16, v11
	v_and_b32_e32 v7, 0xffff0000, v11
	v_pk_fma_f32 v[4:5], v[16:17], v[6:7], v[4:5] op_sel_hi:[0,1,1]
	v_cvt_pk_bf16_f32 v3, v4, v5
	v_lshlrev_b64 v[4:5], 15, v[32:33]
	v_lshl_add_u64 v[4:5], v[34:35], 0, v[4:5]
	global_store_dwordx4 v[4:5], v[0:3], off
	s_waitcnt lgkmcnt(0)
	s_barrier
